# phase 4 weight-conversion share re-dealt: one item per wave for bx<192, the rest to the HGRN quarter
# speedup vs baseline: 1.0058x; 1.0058x over previous
; #define LAS __attribute__((address_space(3)))
; __device__ __forceinline__ void p0_items(const Args& a, LAS float* scr, int first, int last, int w, int nw, int lane) {
;     unsigned char* ws = a.ws;
;     auto desc = [&](int it) -> P0Desc {
;         int mi = 0;
; #pragma unroll
;         for (int j = 1; j < 9; ++j) mi += (it >= P0TAB[j].first) ? 1 : 0;
;         const P0Tab t = P0TAB[mi];
;         P0Desc d; d.W = a.in[t.in_w]; d.WT = (bf16*)(ws + t.wt_off); d.gain = t.in_g >= 0 ? a.in[t.in_g] : nullptr; d.scale = t.scale; d.K = t.K; d.N = t.N; d.mode = t.mode; d.item = it - t.first;
;         return d;
;     };
;     float va[32], vb[32]; int it = first + w;
;     P0Desc da = desc(it < last ? it : first), db = da;
; __global__ void __launch_bounds__(NT, 2) hymba_fwd(Args args) {
;     ...
;     if (IN(4)) p0_items(args, (LAS float*)(lds + wave * 16384), P0_MID, P0_GU2, gw, NGW, lane);
.LBB0_652:
	s_mov_b32 s98, s58
	s_cmpk_lg_i32 s3, 0x100
	s_cbranch_scc1 .Lp4_dealt
	v_readfirstlane_b32 s99, v209
	s_lshr_b32 s99, s99, 6
	s_cmpk_lt_u32 s2, 0xc0
	s_cbranch_scc0 .Lp4_deal_hg
	s_lshl_b32 s24, s2, 3
	s_add_i32 s24, s24, s99
	s_movk_i32 s98, 0x1000
	s_branch .Lp4_dealt
.Lp4_deal_hg:
	s_sub_i32 s24, s2, 0xc0
	s_lshl_b32 s24, s24, 3
	s_add_i32 s24, s24, s99
	s_addk_i32 s24, 0x600
	s_movk_i32 s98, 0x200

; __device__ __forceinline__ void p0_load(const P0Desc& d, float (&v)[32], int lane) {
;     const int nblk = d.N / 32, kb = d.item / nblk, nb = d.item % nblk, k0 = 64 * kb, n0 = 32 * nb;
;     const float* p = d.W + (size_t)(k0 + (lane >> 5)) * d.N + n0 + (lane & 31);
; #pragma unroll
;     for (int i = 0; i < 32; ++i) v[i] = __builtin_nontemporal_load(p + (size_t)(2 * i) * d.N);
; }
; __device__ __forceinline__ void p0_items(const Args& a, LAS float* scr, int first, int last, int w, int nw, int lane) {
;     ...
;     float va[32], vb[32]; int it = first + w;
;     P0Desc da = desc(it < last ? it : first), db = da;
;     if (it < last) p0_load(da, va, lane);
.LBB0_654:
	s_andn2_b64 vcc, exec, s[4:5]
	s_cbranch_vccnz .LBB0_689
	s_load_dwordx4 s[4:7], s[12:13], 0x0
	s_load_dwordx2 s[20:21], s[0:1], 0xb0
	s_load_dwordx2 s[18:19], s[16:17], 0x0
	s_load_dword s8, s[12:13], 0x10
	s_lshl_b32 s9, s88, 14
	s_add_i32 s9, s9, 0
	s_waitcnt lgkmcnt(0)
	s_sub_i32 s7, s40, s7
	s_add_u32 s28, s20, s18
	s_addc_u32 s29, s21, s19
	s_ashr_i32 s13, s5, 31
	s_lshr_b32 s12, s13, 27
	s_add_i32 s12, s5, s12
	s_ashr_i32 s12, s12, 5
	s_abs_i32 s16, s12
	v_cvt_f32_u32_e32 v0, s16
	s_sub_i32 s19, 0, s16
	s_abs_i32 s17, s7
	s_xor_b32 s18, s7, s12
	v_rcp_iflag_f32_e32 v0, v0
	s_ashr_i32 s18, s18, 31
	s_load_dwordx2 s[10:11], s[10:11], 0x0
	v_lshrrev_b32_e32 v39, 5, v208
	v_mul_f32_e32 v0, 0x4f7ffffe, v0
	v_cvt_u32_f32_e32 v0, v0
	v_and_b32_e32 v38, 31, v209
	v_mov_b32_e32 v41, 0
	v_lshlrev_b32_e32 v40, 2, v38
	v_readfirstlane_b32 s22, v0
	s_mul_i32 s19, s19, s22
	s_mul_hi_u32 s19, s22, s19
	s_add_i32 s22, s22, s19
	s_mul_hi_u32 s19, s17, s22
	s_mul_i32 s22, s19, s16
	s_sub_i32 s17, s17, s22
	s_add_i32 s25, s19, 1
	s_sub_i32 s22, s17, s16
	s_cmp_ge_u32 s17, s16
	s_cselect_b32 s19, s25, s19
	s_cselect_b32 s17, s22, s17
	s_add_i32 s22, s19, 1
	s_cmp_ge_u32 s17, s16
	s_cselect_b32 s16, s22, s19
	s_xor_b32 s16, s16, s18
	s_sub_i32 s17, s16, s18
	s_mul_i32 s12, s17, s12
	s_sub_i32 s12, s7, s12
	v_lshl_or_b32 v0, s17, 6, v39
	s_lshl_b32 s16, s12, 5
	v_mad_i64_i32 v[0:1], s[18:19], v0, s5, 0
	s_waitcnt lgkmcnt(0)
	v_lshl_add_u64 v[0:1], v[0:1], 2, s[10:11]
	s_ashr_i32 s17, s16, 31
	s_mov_b32 s12, s5
	v_lshl_add_u64 v[0:1], s[16:17], 2, v[0:1]
	v_lshl_add_u64 v[0:1], v[0:1], 0, v[40:41]
	s_lshl_b64 s[10:11], s[12:13], 3
	v_lshl_add_u64 v[16:17], v[0:1], 0, s[10:11]
	v_lshl_add_u64 v[18:19], v[16:17], 0, s[10:11]
	v_lshl_add_u64 v[20:21], v[18:19], 0, s[10:11]
	v_lshl_add_u64 v[22:23], v[20:21], 0, s[10:11]
	v_lshl_add_u64 v[24:25], v[22:23], 0, s[10:11]
	v_lshl_add_u64 v[26:27], v[24:25], 0, s[10:11]
	v_lshl_add_u64 v[28:29], v[26:27], 0, s[10:11]
	v_lshl_add_u64 v[30:31], v[28:29], 0, s[10:11]
	v_lshl_add_u64 v[32:33], v[30:31], 0, s[10:11]
	v_lshl_add_u64 v[34:35], v[32:33], 0, s[10:11]
	v_lshl_add_u64 v[36:37], v[34:35], 0, s[10:11]
	v_lshl_add_u64 v[44:45], v[36:37], 0, s[10:11]
	v_lshl_add_u64 v[84:85], v[44:45], 0, s[10:11]
	v_lshl_add_u64 v[86:87], v[84:85], 0, s[10:11]
	v_lshl_add_u64 v[88:89], v[86:87], 0, s[10:11]
	v_lshl_add_u64 v[90:91], v[88:89], 0, s[10:11]
	v_lshl_add_u64 v[92:93], v[90:91], 0, s[10:11]
	v_lshl_add_u64 v[94:95], v[92:93], 0, s[10:11]
	v_lshl_add_u64 v[96:97], v[94:95], 0, s[10:11]
	v_lshl_add_u64 v[98:99], v[96:97], 0, s[10:11]
	v_lshl_add_u64 v[100:101], v[98:99], 0, s[10:11]
	v_lshl_add_u64 v[102:103], v[100:101], 0, s[10:11]
	v_lshl_add_u64 v[104:105], v[102:103], 0, s[10:11]
	v_lshl_add_u64 v[106:107], v[104:105], 0, s[10:11]
	v_lshl_add_u64 v[108:109], v[106:107], 0, s[10:11]
	v_lshl_add_u64 v[110:111], v[108:109], 0, s[10:11]
	v_lshl_add_u64 v[112:113], v[110:111], 0, s[10:11]
	v_lshl_add_u64 v[114:115], v[112:113], 0, s[10:11]
	v_lshl_add_u64 v[116:117], v[114:115], 0, s[10:11]
	v_and_b32_e32 v4, 7, v209
	v_lshrrev_b32_e32 v43, 3, v208
	v_lshl_add_u64 v[118:119], v[116:117], 0, s[10:11]
	v_add_u32_e32 v2, s9, v40
	v_mul_u32_u24_e32 v3, 0x84, v39
	v_lshlrev_b32_e32 v42, 3, v4
	v_mul_u32_u24_e32 v4, 0x420, v4
	v_lshlrev_b32_e32 v5, 2, v43
	v_lshl_add_u64 v[120:121], v[118:119], 0, s[10:11]
	v_add3_u32 v46, s9, v4, v5
	v_add_u32_e32 v50, v2, v3
	global_load_dword v0, v[0:1], off nt
	s_nop 0
	global_load_dword v1, v[16:17], off nt
	global_load_dword v2, v[18:19], off nt
	global_load_dword v3, v[20:21], off nt
	global_load_dword v4, v[22:23], off nt
	global_load_dword v5, v[24:25], off nt
	global_load_dword v6, v[26:27], off nt
	global_load_dword v7, v[28:29], off nt
	global_load_dword v8, v[30:31], off nt
	global_load_dword v9, v[32:33], off nt
	global_load_dword v10, v[34:35], off nt
	global_load_dword v11, v[36:37], off nt
	global_load_dword v12, v[44:45], off nt
	global_load_dword v13, v[84:85], off nt
	global_load_dword v14, v[86:87], off nt
	global_load_dword v15, v[88:89], off nt
	global_load_dword v16, v[90:91], off nt
	global_load_dword v17, v[92:93], off nt
	global_load_dword v18, v[94:95], off nt
	global_load_dword v19, v[96:97], off nt
	global_load_dword v20, v[98:99], off nt
	global_load_dword v21, v[100:101], off nt
	global_load_dword v22, v[102:103], off nt
	global_load_dword v23, v[104:105], off nt
	global_load_dword v24, v[106:107], off nt
	global_load_dword v25, v[108:109], off nt
	global_load_dword v26, v[110:111], off nt
	global_load_dword v27, v[112:113], off nt
	global_load_dword v28, v[114:115], off nt
	global_load_dword v29, v[116:117], off nt
	global_load_dword v30, v[118:119], off nt
	global_load_dword v31, v[120:121], off nt
	s_mov_b32 s23, 0
	v_or_b32_e32 v47, 8, v43
	v_or_b32_e32 v48, 16, v43
	v_or_b32_e32 v49, 24, v43
	s_lshl_b32 s25, s98, 1
	v_lshlrev_b32_e32 v40, 1, v42
	s_mov_b64 s[34:35], s[28:29]
	s_mov_b64 s[30:31], s[26:27]
	s_mov_b32 s19, s7
	s_mov_b32 s12, s8
	s_mov_b32 s13, s4
	s_mov_b32 s17, s5
	s_mov_b32 s18, s6
	s_branch .LBB0_658
; #define LAS __attribute__((address_space(3)))
; __device__ __forceinline__ unsigned pk2(float lo, float hi) { return pg8::cvt_pk_bf16(lo, hi); }
; #define LDS_WAIT() asm volatile("s_waitcnt lgkmcnt(0)" ::: "memory")
; __device__ __forceinline__ void p0_store(const P0Desc& d, const float (&v)[32], LAS float* scr, int lane) {
;     const int nblk = d.N / 32, kb = d.item / nblk, nb = d.item % nblk, k0 = 64 * kb, n0 = 32 * nb;
; #pragma unroll
;     for (int i = 0; i < 32; ++i) scr[(2 * i + (lane >> 5)) * 33 + (lane & 31)] = v[i];
;     LDS_WAIT(); asm volatile("" ::: "memory");
;     const int c = lane & 7; const int r0 = rowmap(d.mode, n0, d.N);
;     f32x4 g0 = {d.scale, d.scale, d.scale, d.scale}, g1 = g0;
;     if (d.gain) { g0 = *(const f32x4*)(d.gain + k0 + 8 * c) * d.scale; g1 = *(const f32x4*)(d.gain + k0 + 8 * c + 4) * d.scale; }
; #pragma unroll
;     for (int j = 0; j < 4; ++j) { const int n = (lane >> 3) + 8 * j; const LAS float* q = scr + (8 * c) * 33 + n;
;         v4u o; o.x = pk2(q[0 * 33] * g0[0], q[1 * 33] * g0[1]); o.y = pk2(q[2 * 33] * g0[2], q[3 * 33] * g0[3]); o.z = pk2(q[4 * 33] * g1[0], q[5 * 33] * g1[1]); o.w = pk2(q[6 * 33] * g1[2], q[7 * 33] * g1[3]);
;         pg8::st_wt16(d.WT + (size_t)(r0 + n) * d.K + k0 + 8 * c, o); }
;     LDS_WAIT(); asm volatile("" ::: "memory");
; __device__ __forceinline__ void p0_items(const Args& a, LAS float* scr, int first, int last, int w, int nw, int lane) {
;     ...
;     while (it < last) {
;         const int n1 = it + nw; if (n1 < last) { db = desc(n1); p0_load(db, vb, lane); }
;         p0_store(da, va, scr, lane);
;         if (n1 >= last) break;
;         const int n2 = n1 + nw; if (n2 < last) { da = desc(n2); p0_load(da, va, lane); }
;         p0_store(db, vb, scr, lane);
;         it = n2;
.LBB0_656:
	ds_read2_b32 v[88:89], v46 offset1:8
	ds_read2_b32 v[90:91], v46 offset0:33 offset1:41
	ds_read2_b32 v[92:93], v46 offset0:66 offset1:74
	ds_read2_b32 v[94:95], v46 offset0:99 offset1:107
	ds_read2_b32 v[96:97], v46 offset0:132 offset1:140
	ds_read2_b32 v[98:99], v46 offset0:165 offset1:173
	ds_read2_b32 v[100:101], v46 offset0:198 offset1:206
	ds_read2_b32 v[102:103], v46 offset0:231 offset1:239
	s_waitcnt lgkmcnt(7)
	v_mov_b32_e32 v84, v88
	s_waitcnt lgkmcnt(6)
	v_mov_b32_e32 v85, v90
	s_waitcnt lgkmcnt(5)
	v_mov_b32_e32 v86, v92
	s_waitcnt lgkmcnt(4)
	v_mov_b32_e32 v87, v94
	v_pk_mul_f32 v[84:85], v[34:35], v[84:85]
	v_pk_mul_f32 v[86:87], v[44:45], v[86:87]
	v_cvt_pk_bf16_f32 v84, v84, v85
	v_cvt_pk_bf16_f32 v85, v86, v87
	v_mov_b32_e32 v33, v83
	s_waitcnt lgkmcnt(3)
	v_mov_b32_e32 v86, v96
	s_waitcnt lgkmcnt(2)
	v_mov_b32_e32 v87, v98
	s_waitcnt lgkmcnt(1)
	v_mov_b32_e32 v104, v100
	s_waitcnt lgkmcnt(0)
	v_mov_b32_e32 v105, v102
	v_pk_mul_f32 v[86:87], v[32:33], v[86:87]
	v_pk_mul_f32 v[104:105], v[36:37], v[104:105]
	v_add_u32_e32 v83, s16, v43
	v_cvt_pk_bf16_f32 v86, v86, v87
	v_cvt_pk_bf16_f32 v87, v104, v105
	v_mad_i64_i32 v[104:105], s[10:11], v83, s9, 0
	v_lshl_add_u64 v[104:105], v[104:105], 1, s[28:29]
	s_lshl_b64 s[10:11], s[36:37], 1
	v_lshl_add_u64 v[104:105], v[104:105], 0, s[10:11]
	v_lshl_add_u64 v[104:105], v[104:105], 0, v[40:41]
	v_mov_b32_e32 v90, v89
	v_mov_b32_e32 v94, v93
	global_store_dwordx4 v[104:105], v[84:87], off
	v_mov_b32_e32 v98, v97
	v_mov_b32_e32 v102, v101
	v_pk_mul_f32 v[84:85], v[34:35], v[90:91]
	v_pk_mul_f32 v[86:87], v[44:45], v[94:95]
	v_cvt_pk_bf16_f32 v84, v84, v85
	v_cvt_pk_bf16_f32 v85, v86, v87
	v_pk_mul_f32 v[86:87], v[32:33], v[98:99]
	v_pk_mul_f32 v[88:89], v[36:37], v[102:103]
	v_add_u32_e32 v83, s16, v47
	v_cvt_pk_bf16_f32 v86, v86, v87
	v_cvt_pk_bf16_f32 v87, v88, v89
	v_mad_i64_i32 v[88:89], s[36:37], v83, s9, 0
	v_lshl_add_u64 v[88:89], v[88:89], 1, s[28:29]
	v_lshl_add_u64 v[88:89], v[88:89], 0, s[10:11]
	v_lshl_add_u64 v[88:89], v[88:89], 0, v[40:41]
	ds_read2_b32 v[90:91], v46 offset0:16 offset1:24
	ds_read2_b32 v[92:93], v46 offset0:49 offset1:57
	global_store_dwordx4 v[88:89], v[84:87], off
	ds_read2_b32 v[88:89], v46 offset0:82 offset1:90
	ds_read2_b32 v[94:95], v46 offset0:115 offset1:123
	ds_read2_b32 v[96:97], v46 offset0:148 offset1:156
	ds_read2_b32 v[98:99], v46 offset0:181 offset1:189
	ds_read2_b32 v[100:101], v46 offset0:214 offset1:222
	ds_read2_b32 v[102:103], v46 offset0:247 offset1:255
	s_waitcnt lgkmcnt(7)
	v_mov_b32_e32 v84, v90
	s_waitcnt lgkmcnt(6)
	v_mov_b32_e32 v85, v92
	s_waitcnt lgkmcnt(5)
	v_mov_b32_e32 v86, v88
	s_waitcnt lgkmcnt(4)
	v_mov_b32_e32 v87, v94
	v_pk_mul_f32 v[84:85], v[34:35], v[84:85]
	v_pk_mul_f32 v[86:87], v[44:45], v[86:87]
	v_cvt_pk_bf16_f32 v84, v84, v85
	v_cvt_pk_bf16_f32 v85, v86, v87
	s_waitcnt lgkmcnt(3)
	v_mov_b32_e32 v86, v96
	s_waitcnt lgkmcnt(2)
	v_mov_b32_e32 v87, v98
	s_waitcnt lgkmcnt(1)
	v_mov_b32_e32 v104, v100
	s_waitcnt lgkmcnt(0)
	v_mov_b32_e32 v105, v102
	v_pk_mul_f32 v[86:87], v[32:33], v[86:87]
	v_pk_mul_f32 v[104:105], v[36:37], v[104:105]
	v_add_u32_e32 v83, s16, v48
	v_cvt_pk_bf16_f32 v86, v86, v87
	v_cvt_pk_bf16_f32 v87, v104, v105
	v_mad_i64_i32 v[104:105], s[36:37], v83, s9, 0
	v_lshl_add_u64 v[104:105], v[104:105], 1, s[28:29]
	v_lshl_add_u64 v[104:105], v[104:105], 0, s[10:11]
	v_mov_b32_e32 v98, v97
	v_lshl_add_u64 v[104:105], v[104:105], 0, v[40:41]
	v_pk_mul_f32 v[32:33], v[32:33], v[98:99]
	v_mov_b32_e32 v102, v101
	global_store_dwordx4 v[104:105], v[84:87], off
	v_mov_b32_e32 v92, v91
	v_pk_mul_f32 v[34:35], v[34:35], v[92:93]
	v_cvt_pk_bf16_f32 v86, v32, v33
	v_pk_mul_f32 v[32:33], v[36:37], v[102:103]
	v_mov_b32_e32 v94, v89
	v_cvt_pk_bf16_f32 v87, v32, v33
	v_add_u32_e32 v32, s16, v49
	v_mad_i64_i32 v[32:33], s[36:37], v32, s9, 0
	v_lshl_add_u64 v[32:33], v[32:33], 1, s[28:29]
	v_cvt_pk_bf16_f32 v84, v34, v35
	v_pk_mul_f32 v[34:35], v[44:45], v[94:95]
	v_lshl_add_u64 v[32:33], v[32:33], 0, s[10:11]
	v_cvt_pk_bf16_f32 v85, v34, v35
	v_lshl_add_u64 v[32:33], v[32:33], 0, v[40:41]
	global_store_dwordx4 v[32:33], v[84:87], off
	s_waitcnt lgkmcnt(0)
	s_add_i32 s40, s41, s98
	s_cmpk_gt_i32 s40, 0x2c7f
	s_cselect_b64 s[36:37], -1, 0

; __device__ __forceinline__ void p0_items(const Args& a, LAS float* scr, int first, int last, int w, int nw, int lane) {
;     ...
;     auto desc = [&](int it) -> P0Desc {
;         int mi = 0;
; #pragma unroll
;         for (int j = 1; j < 9; ++j) mi += (it >= P0TAB[j].first) ? 1 : 0;
;         const P0Tab t = P0TAB[mi];
;         P0Desc d; d.W = a.in[t.in_w]; d.WT = (bf16*)(ws + t.wt_off); d.gain = t.in_g >= 0 ? a.in[t.in_g] : nullptr; d.scale = t.scale; d.K = t.K; d.N = t.N; d.mode = t.mode; d.item = it - t.first;
;         return d;
;     };
;     float va[32], vb[32]; int it = first + w;
;     P0Desc da = desc(it < last ? it : first), db = da;
;     if (it < last) p0_load(da, va, lane);
;     while (it < last) {
;         const int n1 = it + nw; if (n1 < last) { db = desc(n1); p0_load(db, vb, lane); }
.LBB0_658:
	s_add_i32 s41, s40, s98
	s_cmpk_lt_i32 s41, 0x2c80
	s_cselect_b64 s[36:37], -1, 0
	s_cmpk_gt_i32 s41, 0x2c7f
	s_cbranch_scc1 .LBB0_662
	s_cmpk_gt_i32 s41, 0xaff
	s_cselect_b64 s[4:5], -1, 0
	s_cmpk_gt_i32 s41, 0xeff
	v_cndmask_b32_e64 v32, 0, 1, s[4:5]
	s_cselect_b64 s[4:5], -1, 0
	s_cmpk_gt_i32 s41, 0x147f
	v_cndmask_b32_e64 v33, 0, 1, s[4:5]
	s_cselect_b64 s[4:5], -1, 0
	v_readfirstlane_b32 s6, v32
	v_readfirstlane_b32 s7, v33
	s_cmp_lg_u64 s[4:5], 0
	s_addc_u32 s6, s6, s7
	s_cmpk_gt_i32 s41, 0x1b7f
	s_cselect_b64 s[4:5], -1, 0
	v_cndmask_b32_e64 v32, 0, 1, s[4:5]
	s_nop 0
	v_readfirstlane_b32 s4, v32
	s_add_u32 s6, s6, s4
	s_addc_u32 s7, 0, 0
	s_cmpk_gt_i32 s41, 0x1d7f
	s_cselect_b64 s[4:5], -1, 0
	v_cndmask_b32_e64 v32, 0, 1, s[4:5]
	s_nop 0
	v_readfirstlane_b32 s4, v32
	s_add_u32 s6, s6, s4
	s_addc_u32 s7, s7, 0
	s_cmpk_gt_i32 s41, 0x1f7f
	s_cselect_b64 s[4:5], -1, 0
	v_cndmask_b32_e64 v32, 0, 1, s[4:5]
	s_nop 0
	v_readfirstlane_b32 s4, v32
	s_add_u32 s6, s6, s4
	s_addc_u32 s7, s7, 0
	s_cmpk_gt_i32 s41, 0x217f
	s_cselect_b64 s[4:5], -1, 0
	v_cndmask_b32_e64 v32, 0, 1, s[4:5]
	s_nop 0
	v_readfirstlane_b32 s4, v32
	s_add_u32 s16, s6, s4
	s_addc_u32 s4, s7, 0
	s_mul_i32 s4, s4, 40
	s_mul_hi_u32 s5, s16, 40
	s_add_i32 s22, s5, s4
	s_mul_i32 s28, s16, 40
	s_getpc_b64 s[4:5]
	s_add_u32 s4, s4, _ZL5P0TAB@rel32@lo+4
	s_addc_u32 s5, s5, _ZL5P0TAB@rel32@hi+12
	s_add_u32 s38, s4, s28
	s_addc_u32 s39, s5, s22
	s_load_dword s10, s[38:39], 0x0
	s_waitcnt lgkmcnt(0)
	s_ashr_i32 s11, s10, 31
	s_getpc_b64 s[4:5]
	s_add_u32 s4, s4, _ZL5P0TAB@rel32@lo+12
	s_addc_u32 s5, s5, _ZL5P0TAB@rel32@hi+20
	s_add_u32 s8, s4, s28
	s_addc_u32 s9, s5, s22
	s_getpc_b64 s[26:27]
	s_add_u32 s26, s26, _ZL5P0TAB@rel32@lo+36
	s_addc_u32 s27, s27, _ZL5P0TAB@rel32@hi+44
	s_add_u32 s28, s26, s28
	s_load_dwordx4 s[4:7], s[8:9], 0x0
	s_addc_u32 s29, s27, s22
	s_lshl_b64 s[10:11], s[10:11], 3
	s_add_u32 s10, s0, s10
	s_addc_u32 s11, s1, s11
	s_lshl_b64 s[26:27], 1, s16
	s_and_b32 s22, s26, 0xa9
	s_cmp_eq_u64 s[22:23], 0
	s_mov_b64 s[26:27], 0
	s_cbranch_scc1 .LBB0_661
	s_load_dword s22, s[38:39], 0x4
	s_waitcnt lgkmcnt(0)
	s_lshl_b64 s[26:27], s[22:23], 3
	s_add_u32 s26, s0, s26
	s_addc_u32 s27, s1, s27
	s_load_dwordx2 s[26:27], s[26:27], 0x0
